# speedup vs baseline: 1.0221x; 1.0078x over previous
; DI unsigned cvtpk(float lo, float hi) { f32x2_t v = {lo, hi}; bf16x2_t b = __builtin_convertvector(v, bf16x2_t); return __builtin_bit_cast(unsigned, b); }
; DI void ln_row(float* yrow, bf16_t* xb, const float* g, const float* b, int lane, float* yout = nullptr) {
;     f32x4* xr = (f32x4*)yrow + lane; f32x4* xo = yout ? (f32x4*)yout + lane : xr;
;     f32x4 v[4]; float s = 0.f;
; #pragma unroll
;     for (int j = 0; j < 4; ++j) { v[j] = xr[64 * j]; s += (v[j].x + v[j].y) + (v[j].z + v[j].w); }
;     const float mean = wave_sum(s) * (1.f / DM); float s2 = 0.f;
; #pragma unroll
;     for (int j = 0; j < 4; ++j) { v[j] = v[j] - mean; s2 += (v[j].x * v[j].x + v[j].y * v[j].y) + (v[j].z * v[j].z + v[j].w * v[j].w); }
;     const float rstd = 1.f / sqrtf(wave_sum(s2) * (1.f / DM) + EPS);
;     u32x2* o8 = (u32x2*)xb + lane;
; #pragma unroll
;     for (int j = 0; j < 4; ++j) {
;         const f32x4 gg = ((const f32x4*)g)[lane + 64 * j], bb = ((const f32x4*)b)[lane + 64 * j];
;         const f32x4 o = v[j] * rstd * gg + bb;
;         xo[64 * j] = o;
;         u32x2 w; w.x = cvtpk(o.x, o.y); w.y = cvtpk(o.z, o.w); o8[64 * j] = w;
;     }
; }
; DI void ln_phase(unsigned char* lds, int l, int which) {
;     ...
;         int m = gw;
;         for (; m + NGW < MP; m += 2 * NGW) ln_row2(Y + (size_t)m * DM, Y + (size_t)(m + NGW) * DM, XB + (size_t)m * DM, XB + (size_t)(m + NGW) * DM, g, b, lane);
;         if (m < MP) ln_row(Y + (size_t)m * DM, XB + (size_t)m * DM, g, b, lane);
.Lmy_lnp0_n0:
	s_add_i32 s100, s56, 0
	s_min_u32 s100, s100, 43
	s_lshl_b32 s100, s100, 7
	s_add_u32 s100, s48, s100
	s_addc_u32 s101, s49, 0
	global_load_dwordx4 v[110:113], v108, s[100:101]
	s_add_i32 s100, s56, 4
	s_min_u32 s100, s100, 43
	s_lshl_b32 s100, s100, 7
	s_add_u32 s100, s48, s100
	s_addc_u32 s101, s49, 0
	global_load_dwordx4 v[110:113], v108, s[100:101]
	s_add_i32 s56, s56, 4
	s_waitcnt vmcnt(20)
	v_add_f32_e32 v84, v36, v37
	v_add_f32_e32 v85, v38, v39
	v_add_f32_e32 v86, v40, v41
	v_add_f32_e32 v87, v42, v43
	v_add_f32_e32 v88, v44, v45
	v_add_f32_e32 v89, v46, v47
	v_add_f32_e32 v90, v48, v49
	v_add_f32_e32 v91, v50, v51
	v_add_f32_e32 v84, v84, v85
	v_add_f32_e32 v86, v86, v87
	v_add_f32_e32 v88, v88, v89
	v_add_f32_e32 v90, v90, v91
	v_add_f32_e32 v84, v84, v86
	v_add_f32_e32 v88, v88, v90
	v_add_f32_e32 v84, v84, v88
	s_nop 1
	v_add_f32_dpp v84, v84, v84 quad_perm:[1,0,3,2] row_mask:0xf bank_mask:0xf
	s_nop 1
	v_add_f32_dpp v84, v84, v84 quad_perm:[2,3,0,1] row_mask:0xf bank_mask:0xf
	s_nop 1
	v_add_f32_dpp v84, v84, v84 row_half_mirror row_mask:0xf bank_mask:0xf
	s_nop 1
	v_add_f32_dpp v84, v84, v84 row_mirror row_mask:0xf bank_mask:0xf
	s_nop 1
	v_add_f32_dpp v84, v84, v84 row_bcast:15 row_mask:0xa bank_mask:0xf
	s_nop 1
	v_add_f32_dpp v84, v84, v84 row_bcast:31 row_mask:0xc bank_mask:0xf
	s_nop 1
	v_readlane_b32 s55, v84, 63
	s_nop 1
	v_mov_b32_e32 v85, s55
	v_mul_f32_e32 v85, 0x3a800000, v85
	v_sub_f32_e32 v36, v36, v85
	v_sub_f32_e32 v37, v37, v85
	v_sub_f32_e32 v38, v38, v85
	v_sub_f32_e32 v39, v39, v85
	v_sub_f32_e32 v40, v40, v85
	v_sub_f32_e32 v41, v41, v85
	v_sub_f32_e32 v42, v42, v85
	v_sub_f32_e32 v43, v43, v85
	v_sub_f32_e32 v44, v44, v85
	v_sub_f32_e32 v45, v45, v85
	v_sub_f32_e32 v46, v46, v85
	v_sub_f32_e32 v47, v47, v85
	v_sub_f32_e32 v48, v48, v85
	v_sub_f32_e32 v49, v49, v85
	v_sub_f32_e32 v50, v50, v85
	v_sub_f32_e32 v51, v51, v85
	v_mul_f32_e32 v88, v36, v36
	v_mul_f32_e32 v89, v37, v37
	v_mul_f32_e32 v90, v38, v38
	v_mul_f32_e32 v91, v39, v39
	v_fmac_f32_e32 v88, v40, v40
	v_fmac_f32_e32 v89, v41, v41
	v_fmac_f32_e32 v90, v42, v42
	v_fmac_f32_e32 v91, v43, v43
	v_fmac_f32_e32 v88, v44, v44
	v_fmac_f32_e32 v89, v45, v45
	v_fmac_f32_e32 v90, v46, v46
	v_fmac_f32_e32 v91, v47, v47
	v_fmac_f32_e32 v88, v48, v48
	v_fmac_f32_e32 v89, v49, v49
	v_fmac_f32_e32 v90, v50, v50
	v_fmac_f32_e32 v91, v51, v51
	v_add_f32_e32 v88, v88, v89
	v_add_f32_e32 v90, v90, v91
	v_add_f32_e32 v88, v88, v90
	s_nop 1
	v_add_f32_dpp v88, v88, v88 quad_perm:[1,0,3,2] row_mask:0xf bank_mask:0xf
	s_nop 1
	v_add_f32_dpp v88, v88, v88 quad_perm:[2,3,0,1] row_mask:0xf bank_mask:0xf
	s_nop 1
	v_add_f32_dpp v88, v88, v88 row_half_mirror row_mask:0xf bank_mask:0xf
	s_nop 1
	v_add_f32_dpp v88, v88, v88 row_mirror row_mask:0xf bank_mask:0xf
	s_nop 1
	v_add_f32_dpp v88, v88, v88 row_bcast:15 row_mask:0xa bank_mask:0xf
	s_nop 1
	v_add_f32_dpp v88, v88, v88 row_bcast:31 row_mask:0xc bank_mask:0xf
	s_nop 1
	v_readlane_b32 s55, v88, 63
	s_nop 1
	v_mov_b32_e32 v89, s55
	v_fmamk_f32 v89, v89, 0x3a800000, v214
	v_rsq_f32_e32 v90, v89
	s_nop 0
	v_mul_f32_e32 v91, v89, v90
	v_mul_f32_e32 v91, v91, v90
	v_mul_f32_e32 v91, -0.5, v91
	v_add_f32_e32 v91, 0x3fc00000, v91
	v_mul_f32_e32 v90, v90, v91
	v_pk_mul_f32 v[36:37], v[36:37], v[90:91] op_sel_hi:[1,0]
	v_pk_mul_f32 v[38:39], v[38:39], v[90:91] op_sel_hi:[1,0]
	v_pk_mul_f32 v[40:41], v[40:41], v[90:91] op_sel_hi:[1,0]
	v_pk_mul_f32 v[42:43], v[42:43], v[90:91] op_sel_hi:[1,0]
	v_pk_mul_f32 v[44:45], v[44:45], v[90:91] op_sel_hi:[1,0]
	v_pk_mul_f32 v[46:47], v[46:47], v[90:91] op_sel_hi:[1,0]
	v_pk_mul_f32 v[48:49], v[48:49], v[90:91] op_sel_hi:[1,0]
	v_pk_mul_f32 v[50:51], v[50:51], v[90:91] op_sel_hi:[1,0]
	v_pk_fma_f32 v[36:37], v[36:37], v[4:5], v[20:21]
	v_pk_fma_f32 v[38:39], v[38:39], v[6:7], v[22:23]
	v_pk_fma_f32 v[40:41], v[40:41], v[8:9], v[24:25]
	v_pk_fma_f32 v[42:43], v[42:43], v[10:11], v[26:27]
	v_pk_fma_f32 v[44:45], v[44:45], v[12:13], v[28:29]
	v_pk_fma_f32 v[46:47], v[46:47], v[14:15], v[30:31]
	v_pk_fma_f32 v[48:49], v[48:49], v[16:17], v[32:33]
	v_pk_fma_f32 v[50:51], v[50:51], v[18:19], v[34:35]
	v_cvt_pk_bf16_f32 v100, v36, v37
	v_cvt_pk_bf16_f32 v101, v38, v39
	v_cvt_pk_bf16_f32 v102, v40, v41
	v_cvt_pk_bf16_f32 v103, v42, v43
	v_cvt_pk_bf16_f32 v104, v44, v45
	v_cvt_pk_bf16_f32 v105, v46, v47
	v_cvt_pk_bf16_f32 v106, v48, v49
	v_cvt_pk_bf16_f32 v107, v50, v51
	global_store_dwordx4 v2, v[36:39], s[8:9] nt
	global_store_dwordx4 v2, v[40:43], s[8:9] offset:1024 nt
	global_store_dwordx4 v2, v[44:47], s[8:9] offset:2048 nt
	global_store_dwordx4 v2, v[48:51], s[8:9] offset:3072 nt
	global_store_dwordx2 v3, v[100:101], s[10:11] nt
	global_store_dwordx2 v3, v[102:103], s[10:11] offset:512 nt
	global_store_dwordx2 v3, v[104:105], s[10:11] offset:1024 nt
	global_store_dwordx2 v3, v[106:107], s[10:11] offset:1536 nt
	s_add_u32 s8, s8, s34
	s_addc_u32 s9, s9, 0
	s_add_u32 s10, s10, s35
	s_addc_u32 s11, s11, 0
	s_add_i32 s4, s4, s5
	s_cmp_ge_i32 s4, 0x8000
	s_cbranch_scc1 .Lmy_lnp0_done

; DI unsigned cvtpk(float lo, float hi) { f32x2_t v = {lo, hi}; bf16x2_t b = __builtin_convertvector(v, bf16x2_t); return __builtin_bit_cast(unsigned, b); }
; DI void ln_row(float* yrow, bf16_t* xb, const float* g, const float* b, int lane, float* yout = nullptr) {
;     f32x4* xr = (f32x4*)yrow + lane; f32x4* xo = yout ? (f32x4*)yout + lane : xr;
;     f32x4 v[4]; float s = 0.f;
; #pragma unroll
;     for (int j = 0; j < 4; ++j) { v[j] = xr[64 * j]; s += (v[j].x + v[j].y) + (v[j].z + v[j].w); }
;     const float mean = wave_sum(s) * (1.f / DM); float s2 = 0.f;
; #pragma unroll
;     for (int j = 0; j < 4; ++j) { v[j] = v[j] - mean; s2 += (v[j].x * v[j].x + v[j].y * v[j].y) + (v[j].z * v[j].z + v[j].w * v[j].w); }
;     const float rstd = 1.f / sqrtf(wave_sum(s2) * (1.f / DM) + EPS);
;     u32x2* o8 = (u32x2*)xb + lane;
; #pragma unroll
;     for (int j = 0; j < 4; ++j) {
;         const f32x4 gg = ((const f32x4*)g)[lane + 64 * j], bb = ((const f32x4*)b)[lane + 64 * j];
;         const f32x4 o = v[j] * rstd * gg + bb;
;         xo[64 * j] = o;
;         u32x2 w; w.x = cvtpk(o.x, o.y); w.y = cvtpk(o.z, o.w); o8[64 * j] = w;
;     }
; }
; DI void ln_phase(unsigned char* lds, int l, int which) {
;     ...
;         int m = gw;
;         for (; m + NGW < MP; m += 2 * NGW) ln_row2(Y + (size_t)m * DM, Y + (size_t)(m + NGW) * DM, XB + (size_t)m * DM, XB + (size_t)(m + NGW) * DM, g, b, lane);
;         if (m < MP) ln_row(Y + (size_t)m * DM, XB + (size_t)m * DM, g, b, lane);
.Lmy_lnp0_n1:
	s_add_i32 s100, s56, 0
	s_min_u32 s100, s100, 43
	s_lshl_b32 s100, s100, 7
	s_add_u32 s100, s48, s100
	s_addc_u32 s101, s49, 0
	global_load_dwordx4 v[110:113], v108, s[100:101]
	s_add_i32 s100, s56, 4
	s_min_u32 s100, s100, 43
	s_lshl_b32 s100, s100, 7
	s_add_u32 s100, s48, s100
	s_addc_u32 s101, s49, 0
	global_load_dwordx4 v[110:113], v108, s[100:101]
	s_add_i32 s56, s56, 4
	s_waitcnt vmcnt(20)
	v_add_f32_e32 v84, v52, v53
	v_add_f32_e32 v85, v54, v55
	v_add_f32_e32 v86, v56, v57
	v_add_f32_e32 v87, v58, v59
	v_add_f32_e32 v88, v60, v61
	v_add_f32_e32 v89, v62, v63
	v_add_f32_e32 v90, v64, v65
	v_add_f32_e32 v91, v66, v67
	v_add_f32_e32 v84, v84, v85
	v_add_f32_e32 v86, v86, v87
	v_add_f32_e32 v88, v88, v89
	v_add_f32_e32 v90, v90, v91
	v_add_f32_e32 v84, v84, v86
	v_add_f32_e32 v88, v88, v90
	v_add_f32_e32 v84, v84, v88
	s_nop 1
	v_add_f32_dpp v84, v84, v84 quad_perm:[1,0,3,2] row_mask:0xf bank_mask:0xf
	s_nop 1
	v_add_f32_dpp v84, v84, v84 quad_perm:[2,3,0,1] row_mask:0xf bank_mask:0xf
	s_nop 1
	v_add_f32_dpp v84, v84, v84 row_half_mirror row_mask:0xf bank_mask:0xf
	s_nop 1
	v_add_f32_dpp v84, v84, v84 row_mirror row_mask:0xf bank_mask:0xf
	s_nop 1
	v_add_f32_dpp v84, v84, v84 row_bcast:15 row_mask:0xa bank_mask:0xf
	s_nop 1
	v_add_f32_dpp v84, v84, v84 row_bcast:31 row_mask:0xc bank_mask:0xf
	s_nop 1
	v_readlane_b32 s55, v84, 63
	s_nop 1
	v_mov_b32_e32 v85, s55
	v_mul_f32_e32 v85, 0x3a800000, v85
	v_sub_f32_e32 v52, v52, v85
	v_sub_f32_e32 v53, v53, v85
	v_sub_f32_e32 v54, v54, v85
	v_sub_f32_e32 v55, v55, v85
	v_sub_f32_e32 v56, v56, v85
	v_sub_f32_e32 v57, v57, v85
	v_sub_f32_e32 v58, v58, v85
	v_sub_f32_e32 v59, v59, v85
	v_sub_f32_e32 v60, v60, v85
	v_sub_f32_e32 v61, v61, v85
	v_sub_f32_e32 v62, v62, v85
	v_sub_f32_e32 v63, v63, v85
	v_sub_f32_e32 v64, v64, v85
	v_sub_f32_e32 v65, v65, v85
	v_sub_f32_e32 v66, v66, v85
	v_sub_f32_e32 v67, v67, v85
	v_mul_f32_e32 v88, v52, v52
	v_mul_f32_e32 v89, v53, v53
	v_mul_f32_e32 v90, v54, v54
	v_mul_f32_e32 v91, v55, v55
	v_fmac_f32_e32 v88, v56, v56
	v_fmac_f32_e32 v89, v57, v57
	v_fmac_f32_e32 v90, v58, v58
	v_fmac_f32_e32 v91, v59, v59
	v_fmac_f32_e32 v88, v60, v60
	v_fmac_f32_e32 v89, v61, v61
	v_fmac_f32_e32 v90, v62, v62
	v_fmac_f32_e32 v91, v63, v63
	v_fmac_f32_e32 v88, v64, v64
	v_fmac_f32_e32 v89, v65, v65
	v_fmac_f32_e32 v90, v66, v66
	v_fmac_f32_e32 v91, v67, v67
	v_add_f32_e32 v88, v88, v89
	v_add_f32_e32 v90, v90, v91
	v_add_f32_e32 v88, v88, v90
	s_nop 1
	v_add_f32_dpp v88, v88, v88 quad_perm:[1,0,3,2] row_mask:0xf bank_mask:0xf
	s_nop 1
	v_add_f32_dpp v88, v88, v88 quad_perm:[2,3,0,1] row_mask:0xf bank_mask:0xf
	s_nop 1
	v_add_f32_dpp v88, v88, v88 row_half_mirror row_mask:0xf bank_mask:0xf
	s_nop 1
	v_add_f32_dpp v88, v88, v88 row_mirror row_mask:0xf bank_mask:0xf
	s_nop 1
	v_add_f32_dpp v88, v88, v88 row_bcast:15 row_mask:0xa bank_mask:0xf
	s_nop 1
	v_add_f32_dpp v88, v88, v88 row_bcast:31 row_mask:0xc bank_mask:0xf
	s_nop 1
	v_readlane_b32 s55, v88, 63
	s_nop 1
	v_mov_b32_e32 v89, s55
	v_fmamk_f32 v89, v89, 0x3a800000, v214
	v_rsq_f32_e32 v90, v89
	s_nop 0
	v_mul_f32_e32 v91, v89, v90
	v_mul_f32_e32 v91, v91, v90
	v_mul_f32_e32 v91, -0.5, v91
	v_add_f32_e32 v91, 0x3fc00000, v91
	v_mul_f32_e32 v90, v90, v91
	v_pk_mul_f32 v[52:53], v[52:53], v[90:91] op_sel_hi:[1,0]
	v_pk_mul_f32 v[54:55], v[54:55], v[90:91] op_sel_hi:[1,0]
	v_pk_mul_f32 v[56:57], v[56:57], v[90:91] op_sel_hi:[1,0]
	v_pk_mul_f32 v[58:59], v[58:59], v[90:91] op_sel_hi:[1,0]
	v_pk_mul_f32 v[60:61], v[60:61], v[90:91] op_sel_hi:[1,0]
	v_pk_mul_f32 v[62:63], v[62:63], v[90:91] op_sel_hi:[1,0]
	v_pk_mul_f32 v[64:65], v[64:65], v[90:91] op_sel_hi:[1,0]
	v_pk_mul_f32 v[66:67], v[66:67], v[90:91] op_sel_hi:[1,0]
	v_pk_fma_f32 v[52:53], v[52:53], v[4:5], v[20:21]
	v_pk_fma_f32 v[54:55], v[54:55], v[6:7], v[22:23]
	v_pk_fma_f32 v[56:57], v[56:57], v[8:9], v[24:25]
	v_pk_fma_f32 v[58:59], v[58:59], v[10:11], v[26:27]
	v_pk_fma_f32 v[60:61], v[60:61], v[12:13], v[28:29]
	v_pk_fma_f32 v[62:63], v[62:63], v[14:15], v[30:31]
	v_pk_fma_f32 v[64:65], v[64:65], v[16:17], v[32:33]
	v_pk_fma_f32 v[66:67], v[66:67], v[18:19], v[34:35]
	v_cvt_pk_bf16_f32 v100, v52, v53
	v_cvt_pk_bf16_f32 v101, v54, v55
	v_cvt_pk_bf16_f32 v102, v56, v57
	v_cvt_pk_bf16_f32 v103, v58, v59
	v_cvt_pk_bf16_f32 v104, v60, v61
	v_cvt_pk_bf16_f32 v105, v62, v63
	v_cvt_pk_bf16_f32 v106, v64, v65
	v_cvt_pk_bf16_f32 v107, v66, v67
	global_store_dwordx4 v2, v[52:55], s[8:9] nt
	global_store_dwordx4 v2, v[56:59], s[8:9] offset:1024 nt
	global_store_dwordx4 v2, v[60:63], s[8:9] offset:2048 nt
	global_store_dwordx4 v2, v[64:67], s[8:9] offset:3072 nt
	global_store_dwordx2 v3, v[100:101], s[10:11] nt
	global_store_dwordx2 v3, v[102:103], s[10:11] offset:512 nt
	global_store_dwordx2 v3, v[104:105], s[10:11] offset:1024 nt
	global_store_dwordx2 v3, v[106:107], s[10:11] offset:1536 nt
	s_add_u32 s8, s8, s34
	s_addc_u32 s9, s9, 0
	s_add_u32 s10, s10, s35
	s_addc_u32 s11, s11, 0
	s_add_i32 s4, s4, s5
	s_cmp_ge_i32 s4, 0x8000
	s_cbranch_scc1 .Lmy_lnp0_done

; DI unsigned cvtpk(float lo, float hi) { f32x2_t v = {lo, hi}; bf16x2_t b = __builtin_convertvector(v, bf16x2_t); return __builtin_bit_cast(unsigned, b); }
; DI void ln_row(float* yrow, bf16_t* xb, const float* g, const float* b, int lane, float* yout = nullptr) {
;     f32x4* xr = (f32x4*)yrow + lane; f32x4* xo = yout ? (f32x4*)yout + lane : xr;
;     f32x4 v[4]; float s = 0.f;
; #pragma unroll
;     for (int j = 0; j < 4; ++j) { v[j] = xr[64 * j]; s += (v[j].x + v[j].y) + (v[j].z + v[j].w); }
;     const float mean = wave_sum(s) * (1.f / DM); float s2 = 0.f;
; #pragma unroll
;     for (int j = 0; j < 4; ++j) { v[j] = v[j] - mean; s2 += (v[j].x * v[j].x + v[j].y * v[j].y) + (v[j].z * v[j].z + v[j].w * v[j].w); }
;     const float rstd = 1.f / sqrtf(wave_sum(s2) * (1.f / DM) + EPS);
;     u32x2* o8 = (u32x2*)xb + lane;
; #pragma unroll
;     for (int j = 0; j < 4; ++j) {
;         const f32x4 gg = ((const f32x4*)g)[lane + 64 * j], bb = ((const f32x4*)b)[lane + 64 * j];
;         const f32x4 o = v[j] * rstd * gg + bb;
;         xo[64 * j] = o;
;         u32x2 w; w.x = cvtpk(o.x, o.y); w.y = cvtpk(o.z, o.w); o8[64 * j] = w;
;     }
; }
; DI void ln_phase(unsigned char* lds, int l, int which) {
;     ...
;         int m = gw;
;         for (; m + NGW < MP; m += 2 * NGW) ln_row2(Y + (size_t)m * DM, Y + (size_t)(m + NGW) * DM, XB + (size_t)m * DM, XB + (size_t)(m + NGW) * DM, g, b, lane);
;         if (m < MP) ln_row(Y + (size_t)m * DM, XB + (size_t)m * DM, g, b, lane);
.Lmy_lnp0_n2:
	s_add_i32 s100, s56, 0
	s_min_u32 s100, s100, 43
	s_lshl_b32 s100, s100, 7
	s_add_u32 s100, s48, s100
	s_addc_u32 s101, s49, 0
	global_load_dwordx4 v[110:113], v108, s[100:101]
	s_add_i32 s100, s56, 4
	s_min_u32 s100, s100, 43
	s_lshl_b32 s100, s100, 7
	s_add_u32 s100, s48, s100
	s_addc_u32 s101, s49, 0
	global_load_dwordx4 v[110:113], v108, s[100:101]
	s_add_i32 s56, s56, 4
	s_waitcnt vmcnt(20)
	v_add_f32_e32 v84, v68, v69
	v_add_f32_e32 v85, v70, v71
	v_add_f32_e32 v86, v72, v73
	v_add_f32_e32 v87, v74, v75
	v_add_f32_e32 v88, v76, v77
	v_add_f32_e32 v89, v78, v79
	v_add_f32_e32 v90, v80, v81
	v_add_f32_e32 v91, v82, v83
	v_add_f32_e32 v84, v84, v85
	v_add_f32_e32 v86, v86, v87
	v_add_f32_e32 v88, v88, v89
	v_add_f32_e32 v90, v90, v91
	v_add_f32_e32 v84, v84, v86
	v_add_f32_e32 v88, v88, v90
	v_add_f32_e32 v84, v84, v88
	s_nop 1
	v_add_f32_dpp v84, v84, v84 quad_perm:[1,0,3,2] row_mask:0xf bank_mask:0xf
	s_nop 1
	v_add_f32_dpp v84, v84, v84 quad_perm:[2,3,0,1] row_mask:0xf bank_mask:0xf
	s_nop 1
	v_add_f32_dpp v84, v84, v84 row_half_mirror row_mask:0xf bank_mask:0xf
	s_nop 1
	v_add_f32_dpp v84, v84, v84 row_mirror row_mask:0xf bank_mask:0xf
	s_nop 1
	v_add_f32_dpp v84, v84, v84 row_bcast:15 row_mask:0xa bank_mask:0xf
	s_nop 1
	v_add_f32_dpp v84, v84, v84 row_bcast:31 row_mask:0xc bank_mask:0xf
	s_nop 1
	v_readlane_b32 s55, v84, 63
	s_nop 1
	v_mov_b32_e32 v85, s55
	v_mul_f32_e32 v85, 0x3a800000, v85
	v_sub_f32_e32 v68, v68, v85
	v_sub_f32_e32 v69, v69, v85
	v_sub_f32_e32 v70, v70, v85
	v_sub_f32_e32 v71, v71, v85
	v_sub_f32_e32 v72, v72, v85
	v_sub_f32_e32 v73, v73, v85
	v_sub_f32_e32 v74, v74, v85
	v_sub_f32_e32 v75, v75, v85
	v_sub_f32_e32 v76, v76, v85
	v_sub_f32_e32 v77, v77, v85
	v_sub_f32_e32 v78, v78, v85
	v_sub_f32_e32 v79, v79, v85
	v_sub_f32_e32 v80, v80, v85
	v_sub_f32_e32 v81, v81, v85
	v_sub_f32_e32 v82, v82, v85
	v_sub_f32_e32 v83, v83, v85
	v_mul_f32_e32 v88, v68, v68
	v_mul_f32_e32 v89, v69, v69
	v_mul_f32_e32 v90, v70, v70
	v_mul_f32_e32 v91, v71, v71
	v_fmac_f32_e32 v88, v72, v72
	v_fmac_f32_e32 v89, v73, v73
	v_fmac_f32_e32 v90, v74, v74
	v_fmac_f32_e32 v91, v75, v75
	v_fmac_f32_e32 v88, v76, v76
	v_fmac_f32_e32 v89, v77, v77
	v_fmac_f32_e32 v90, v78, v78
	v_fmac_f32_e32 v91, v79, v79
	v_fmac_f32_e32 v88, v80, v80
	v_fmac_f32_e32 v89, v81, v81
	v_fmac_f32_e32 v90, v82, v82
	v_fmac_f32_e32 v91, v83, v83
	v_add_f32_e32 v88, v88, v89
	v_add_f32_e32 v90, v90, v91
	v_add_f32_e32 v88, v88, v90
	s_nop 1
	v_add_f32_dpp v88, v88, v88 quad_perm:[1,0,3,2] row_mask:0xf bank_mask:0xf
	s_nop 1
	v_add_f32_dpp v88, v88, v88 quad_perm:[2,3,0,1] row_mask:0xf bank_mask:0xf
	s_nop 1
	v_add_f32_dpp v88, v88, v88 row_half_mirror row_mask:0xf bank_mask:0xf
	s_nop 1
	v_add_f32_dpp v88, v88, v88 row_mirror row_mask:0xf bank_mask:0xf
	s_nop 1
	v_add_f32_dpp v88, v88, v88 row_bcast:15 row_mask:0xa bank_mask:0xf
	s_nop 1
	v_add_f32_dpp v88, v88, v88 row_bcast:31 row_mask:0xc bank_mask:0xf
	s_nop 1
	v_readlane_b32 s55, v88, 63
	s_nop 1
	v_mov_b32_e32 v89, s55
	v_fmamk_f32 v89, v89, 0x3a800000, v214
	v_rsq_f32_e32 v90, v89
	s_nop 0
	v_mul_f32_e32 v91, v89, v90
	v_mul_f32_e32 v91, v91, v90
	v_mul_f32_e32 v91, -0.5, v91
	v_add_f32_e32 v91, 0x3fc00000, v91
	v_mul_f32_e32 v90, v90, v91
	v_pk_mul_f32 v[68:69], v[68:69], v[90:91] op_sel_hi:[1,0]
	v_pk_mul_f32 v[70:71], v[70:71], v[90:91] op_sel_hi:[1,0]
	v_pk_mul_f32 v[72:73], v[72:73], v[90:91] op_sel_hi:[1,0]
	v_pk_mul_f32 v[74:75], v[74:75], v[90:91] op_sel_hi:[1,0]
	v_pk_mul_f32 v[76:77], v[76:77], v[90:91] op_sel_hi:[1,0]
	v_pk_mul_f32 v[78:79], v[78:79], v[90:91] op_sel_hi:[1,0]
	v_pk_mul_f32 v[80:81], v[80:81], v[90:91] op_sel_hi:[1,0]
	v_pk_mul_f32 v[82:83], v[82:83], v[90:91] op_sel_hi:[1,0]
	v_pk_fma_f32 v[68:69], v[68:69], v[4:5], v[20:21]
	v_pk_fma_f32 v[70:71], v[70:71], v[6:7], v[22:23]
	v_pk_fma_f32 v[72:73], v[72:73], v[8:9], v[24:25]
	v_pk_fma_f32 v[74:75], v[74:75], v[10:11], v[26:27]
	v_pk_fma_f32 v[76:77], v[76:77], v[12:13], v[28:29]
	v_pk_fma_f32 v[78:79], v[78:79], v[14:15], v[30:31]
	v_pk_fma_f32 v[80:81], v[80:81], v[16:17], v[32:33]
	v_pk_fma_f32 v[82:83], v[82:83], v[18:19], v[34:35]
	v_cvt_pk_bf16_f32 v100, v68, v69
	v_cvt_pk_bf16_f32 v101, v70, v71
	v_cvt_pk_bf16_f32 v102, v72, v73
	v_cvt_pk_bf16_f32 v103, v74, v75
	v_cvt_pk_bf16_f32 v104, v76, v77
	v_cvt_pk_bf16_f32 v105, v78, v79
	v_cvt_pk_bf16_f32 v106, v80, v81
	v_cvt_pk_bf16_f32 v107, v82, v83
	global_store_dwordx4 v2, v[68:71], s[8:9] nt
	global_store_dwordx4 v2, v[72:75], s[8:9] offset:1024 nt
	global_store_dwordx4 v2, v[76:79], s[8:9] offset:2048 nt
	global_store_dwordx4 v2, v[80:83], s[8:9] offset:3072 nt
	global_store_dwordx2 v3, v[100:101], s[10:11] nt
	global_store_dwordx2 v3, v[102:103], s[10:11] offset:512 nt
	global_store_dwordx2 v3, v[104:105], s[10:11] offset:1024 nt
	global_store_dwordx2 v3, v[106:107], s[10:11] offset:1536 nt
	s_add_u32 s8, s8, s34
	s_addc_u32 s9, s9, 0
	s_add_u32 s10, s10, s35
	s_addc_u32 s11, s11, 0
	s_add_i32 s4, s4, s5
	s_cmp_ge_i32 s4, 0x8000
	s_cbranch_scc1 .Lmy_lnp0_done
	s_branch .Lmy_lnp0_b0

; DI unsigned cvtpk(float lo, float hi) { f32x2_t v = {lo, hi}; bf16x2_t b = __builtin_convertvector(v, bf16x2_t); return __builtin_bit_cast(unsigned, b); }
; DI void ln_row(float* yrow, bf16_t* xb, const float* g, const float* b, int lane, float* yout = nullptr) {
;     f32x4* xr = (f32x4*)yrow + lane; f32x4* xo = yout ? (f32x4*)yout + lane : xr;
;     f32x4 v[4]; float s = 0.f;
; #pragma unroll
;     for (int j = 0; j < 4; ++j) { v[j] = xr[64 * j]; s += (v[j].x + v[j].y) + (v[j].z + v[j].w); }
;     const float mean = wave_sum(s) * (1.f / DM); float s2 = 0.f;
; #pragma unroll
;     for (int j = 0; j < 4; ++j) { v[j] = v[j] - mean; s2 += (v[j].x * v[j].x + v[j].y * v[j].y) + (v[j].z * v[j].z + v[j].w * v[j].w); }
;     const float rstd = 1.f / sqrtf(wave_sum(s2) * (1.f / DM) + EPS);
;     u32x2* o8 = (u32x2*)xb + lane;
; #pragma unroll
;     for (int j = 0; j < 4; ++j) {
;         const f32x4 gg = ((const f32x4*)g)[lane + 64 * j], bb = ((const f32x4*)b)[lane + 64 * j];
;         const f32x4 o = v[j] * rstd * gg + bb;
;         xo[64 * j] = o;
;         u32x2 w; w.x = cvtpk(o.x, o.y); w.y = cvtpk(o.z, o.w); o8[64 * j] = w;
;     }
; }
; DI void ln_phase(unsigned char* lds, int l, int which) {
;     ...
;         int m = gw;
;         for (; m + NGW < MP; m += 2 * NGW) ln_row2(Y + (size_t)m * DM, Y + (size_t)(m + NGW) * DM, XB + (size_t)m * DM, XB + (size_t)(m + NGW) * DM, g, b, lane);
;         if (m < MP) ln_row(Y + (size_t)m * DM, XB + (size_t)m * DM, g, b, lane);
.Lmy_lnp1_n0:
	s_add_i32 s100, s56, 0
	s_min_u32 s100, s100, 15
	s_lshl_b32 s100, s100, 7
	s_add_u32 s100, s48, s100
	s_addc_u32 s101, s49, 0
	global_load_dwordx4 v[110:113], v108, s[100:101]
	s_add_i32 s100, s56, 4
	s_min_u32 s100, s100, 15
	s_lshl_b32 s100, s100, 7
	s_add_u32 s100, s48, s100
	s_addc_u32 s101, s49, 0
	global_load_dwordx4 v[110:113], v108, s[100:101]
	s_add_i32 s56, s56, 4
	s_waitcnt vmcnt(20)
	v_add_f32_e32 v84, v36, v37
	v_add_f32_e32 v85, v38, v39
	v_add_f32_e32 v86, v40, v41
	v_add_f32_e32 v87, v42, v43
	v_add_f32_e32 v88, v44, v45
	v_add_f32_e32 v89, v46, v47
	v_add_f32_e32 v90, v48, v49
	v_add_f32_e32 v91, v50, v51
	v_add_f32_e32 v84, v84, v85
	v_add_f32_e32 v86, v86, v87
	v_add_f32_e32 v88, v88, v89
	v_add_f32_e32 v90, v90, v91
	v_add_f32_e32 v84, v84, v86
	v_add_f32_e32 v88, v88, v90
	v_add_f32_e32 v84, v84, v88
	s_nop 1
	v_add_f32_dpp v84, v84, v84 quad_perm:[1,0,3,2] row_mask:0xf bank_mask:0xf
	s_nop 1
	v_add_f32_dpp v84, v84, v84 quad_perm:[2,3,0,1] row_mask:0xf bank_mask:0xf
	s_nop 1
	v_add_f32_dpp v84, v84, v84 row_half_mirror row_mask:0xf bank_mask:0xf
	s_nop 1
	v_add_f32_dpp v84, v84, v84 row_mirror row_mask:0xf bank_mask:0xf
	s_nop 1
	v_add_f32_dpp v84, v84, v84 row_bcast:15 row_mask:0xa bank_mask:0xf
	s_nop 1
	v_add_f32_dpp v84, v84, v84 row_bcast:31 row_mask:0xc bank_mask:0xf
	s_nop 1
	v_readlane_b32 s55, v84, 63
	s_nop 1
	v_mov_b32_e32 v85, s55
	v_mul_f32_e32 v85, 0x3a800000, v85
	v_sub_f32_e32 v36, v36, v85
	v_sub_f32_e32 v37, v37, v85
	v_sub_f32_e32 v38, v38, v85
	v_sub_f32_e32 v39, v39, v85
	v_sub_f32_e32 v40, v40, v85
	v_sub_f32_e32 v41, v41, v85
	v_sub_f32_e32 v42, v42, v85
	v_sub_f32_e32 v43, v43, v85
	v_sub_f32_e32 v44, v44, v85
	v_sub_f32_e32 v45, v45, v85
	v_sub_f32_e32 v46, v46, v85
	v_sub_f32_e32 v47, v47, v85
	v_sub_f32_e32 v48, v48, v85
	v_sub_f32_e32 v49, v49, v85
	v_sub_f32_e32 v50, v50, v85
	v_sub_f32_e32 v51, v51, v85
	v_mul_f32_e32 v88, v36, v36
	v_mul_f32_e32 v89, v37, v37
	v_mul_f32_e32 v90, v38, v38
	v_mul_f32_e32 v91, v39, v39
	v_fmac_f32_e32 v88, v40, v40
	v_fmac_f32_e32 v89, v41, v41
	v_fmac_f32_e32 v90, v42, v42
	v_fmac_f32_e32 v91, v43, v43
	v_fmac_f32_e32 v88, v44, v44
	v_fmac_f32_e32 v89, v45, v45
	v_fmac_f32_e32 v90, v46, v46
	v_fmac_f32_e32 v91, v47, v47
	v_fmac_f32_e32 v88, v48, v48
	v_fmac_f32_e32 v89, v49, v49
	v_fmac_f32_e32 v90, v50, v50
	v_fmac_f32_e32 v91, v51, v51
	v_add_f32_e32 v88, v88, v89
	v_add_f32_e32 v90, v90, v91
	v_add_f32_e32 v88, v88, v90
	s_nop 1
	v_add_f32_dpp v88, v88, v88 quad_perm:[1,0,3,2] row_mask:0xf bank_mask:0xf
	s_nop 1
	v_add_f32_dpp v88, v88, v88 quad_perm:[2,3,0,1] row_mask:0xf bank_mask:0xf
	s_nop 1
	v_add_f32_dpp v88, v88, v88 row_half_mirror row_mask:0xf bank_mask:0xf
	s_nop 1
	v_add_f32_dpp v88, v88, v88 row_mirror row_mask:0xf bank_mask:0xf
	s_nop 1
	v_add_f32_dpp v88, v88, v88 row_bcast:15 row_mask:0xa bank_mask:0xf
	s_nop 1
	v_add_f32_dpp v88, v88, v88 row_bcast:31 row_mask:0xc bank_mask:0xf
	s_nop 1
	v_readlane_b32 s55, v88, 63
	s_nop 1
	v_mov_b32_e32 v89, s55
	v_fmamk_f32 v89, v89, 0x3a800000, v214
	v_rsq_f32_e32 v90, v89
	s_nop 0
	v_mul_f32_e32 v91, v89, v90
	v_mul_f32_e32 v91, v91, v90
	v_mul_f32_e32 v91, -0.5, v91
	v_add_f32_e32 v91, 0x3fc00000, v91
	v_mul_f32_e32 v90, v90, v91
	v_pk_mul_f32 v[36:37], v[36:37], v[90:91] op_sel_hi:[1,0]
	v_pk_mul_f32 v[38:39], v[38:39], v[90:91] op_sel_hi:[1,0]
	v_pk_mul_f32 v[40:41], v[40:41], v[90:91] op_sel_hi:[1,0]
	v_pk_mul_f32 v[42:43], v[42:43], v[90:91] op_sel_hi:[1,0]
	v_pk_mul_f32 v[44:45], v[44:45], v[90:91] op_sel_hi:[1,0]
	v_pk_mul_f32 v[46:47], v[46:47], v[90:91] op_sel_hi:[1,0]
	v_pk_mul_f32 v[48:49], v[48:49], v[90:91] op_sel_hi:[1,0]
	v_pk_mul_f32 v[50:51], v[50:51], v[90:91] op_sel_hi:[1,0]
	v_pk_fma_f32 v[36:37], v[36:37], v[4:5], v[20:21]
	v_pk_fma_f32 v[38:39], v[38:39], v[6:7], v[22:23]
	v_pk_fma_f32 v[40:41], v[40:41], v[8:9], v[24:25]
	v_pk_fma_f32 v[42:43], v[42:43], v[10:11], v[26:27]
	v_pk_fma_f32 v[44:45], v[44:45], v[12:13], v[28:29]
	v_pk_fma_f32 v[46:47], v[46:47], v[14:15], v[30:31]
	v_pk_fma_f32 v[48:49], v[48:49], v[16:17], v[32:33]
	v_pk_fma_f32 v[50:51], v[50:51], v[18:19], v[34:35]
	v_cvt_pk_bf16_f32 v100, v36, v37
	v_cvt_pk_bf16_f32 v101, v38, v39
	v_cvt_pk_bf16_f32 v102, v40, v41
	v_cvt_pk_bf16_f32 v103, v42, v43
	v_cvt_pk_bf16_f32 v104, v44, v45
	v_cvt_pk_bf16_f32 v105, v46, v47
	v_cvt_pk_bf16_f32 v106, v48, v49
	v_cvt_pk_bf16_f32 v107, v50, v51
	global_store_dwordx4 v2, v[36:39], s[8:9] nt
	global_store_dwordx4 v2, v[40:43], s[8:9] offset:1024 nt
	global_store_dwordx4 v2, v[44:47], s[8:9] offset:2048 nt
	global_store_dwordx4 v2, v[48:51], s[8:9] offset:3072 nt
	global_store_dwordx2 v3, v[100:101], s[10:11] nt
	global_store_dwordx2 v3, v[102:103], s[10:11] offset:512 nt
	global_store_dwordx2 v3, v[104:105], s[10:11] offset:1024 nt
	global_store_dwordx2 v3, v[106:107], s[10:11] offset:1536 nt
	s_add_u32 s8, s8, s34
	s_addc_u32 s9, s9, 0
	s_add_u32 s10, s10, s35
	s_addc_u32 s11, s11, 0
	s_add_i32 s4, s4, s5
	s_cmp_ge_i32 s4, 0x8000
	s_cbranch_scc1 .Lmy_lnp1_done

; DI unsigned cvtpk(float lo, float hi) { f32x2_t v = {lo, hi}; bf16x2_t b = __builtin_convertvector(v, bf16x2_t); return __builtin_bit_cast(unsigned, b); }
; DI void ln_row(float* yrow, bf16_t* xb, const float* g, const float* b, int lane, float* yout = nullptr) {
;     f32x4* xr = (f32x4*)yrow + lane; f32x4* xo = yout ? (f32x4*)yout + lane : xr;
;     f32x4 v[4]; float s = 0.f;
; #pragma unroll
;     for (int j = 0; j < 4; ++j) { v[j] = xr[64 * j]; s += (v[j].x + v[j].y) + (v[j].z + v[j].w); }
;     const float mean = wave_sum(s) * (1.f / DM); float s2 = 0.f;
; #pragma unroll
;     for (int j = 0; j < 4; ++j) { v[j] = v[j] - mean; s2 += (v[j].x * v[j].x + v[j].y * v[j].y) + (v[j].z * v[j].z + v[j].w * v[j].w); }
;     const float rstd = 1.f / sqrtf(wave_sum(s2) * (1.f / DM) + EPS);
;     u32x2* o8 = (u32x2*)xb + lane;
; #pragma unroll
;     for (int j = 0; j < 4; ++j) {
;         const f32x4 gg = ((const f32x4*)g)[lane + 64 * j], bb = ((const f32x4*)b)[lane + 64 * j];
;         const f32x4 o = v[j] * rstd * gg + bb;
;         xo[64 * j] = o;
;         u32x2 w; w.x = cvtpk(o.x, o.y); w.y = cvtpk(o.z, o.w); o8[64 * j] = w;
;     }
; }
; DI void ln_phase(unsigned char* lds, int l, int which) {
;     ...
;         int m = gw;
;         for (; m + NGW < MP; m += 2 * NGW) ln_row2(Y + (size_t)m * DM, Y + (size_t)(m + NGW) * DM, XB + (size_t)m * DM, XB + (size_t)(m + NGW) * DM, g, b, lane);
;         if (m < MP) ln_row(Y + (size_t)m * DM, XB + (size_t)m * DM, g, b, lane);
.Lmy_lnp1_n1:
	s_add_i32 s100, s56, 0
	s_min_u32 s100, s100, 15
	s_lshl_b32 s100, s100, 7
	s_add_u32 s100, s48, s100
	s_addc_u32 s101, s49, 0
	global_load_dwordx4 v[110:113], v108, s[100:101]
	s_add_i32 s100, s56, 4
	s_min_u32 s100, s100, 15
	s_lshl_b32 s100, s100, 7
	s_add_u32 s100, s48, s100
	s_addc_u32 s101, s49, 0
	global_load_dwordx4 v[110:113], v108, s[100:101]
	s_add_i32 s56, s56, 4
	s_waitcnt vmcnt(20)
	v_add_f32_e32 v84, v52, v53
	v_add_f32_e32 v85, v54, v55
	v_add_f32_e32 v86, v56, v57
	v_add_f32_e32 v87, v58, v59
	v_add_f32_e32 v88, v60, v61
	v_add_f32_e32 v89, v62, v63
	v_add_f32_e32 v90, v64, v65
	v_add_f32_e32 v91, v66, v67
	v_add_f32_e32 v84, v84, v85
	v_add_f32_e32 v86, v86, v87
	v_add_f32_e32 v88, v88, v89
	v_add_f32_e32 v90, v90, v91
	v_add_f32_e32 v84, v84, v86
	v_add_f32_e32 v88, v88, v90
	v_add_f32_e32 v84, v84, v88
	s_nop 1
	v_add_f32_dpp v84, v84, v84 quad_perm:[1,0,3,2] row_mask:0xf bank_mask:0xf
	s_nop 1
	v_add_f32_dpp v84, v84, v84 quad_perm:[2,3,0,1] row_mask:0xf bank_mask:0xf
	s_nop 1
	v_add_f32_dpp v84, v84, v84 row_half_mirror row_mask:0xf bank_mask:0xf
	s_nop 1
	v_add_f32_dpp v84, v84, v84 row_mirror row_mask:0xf bank_mask:0xf
	s_nop 1
	v_add_f32_dpp v84, v84, v84 row_bcast:15 row_mask:0xa bank_mask:0xf
	s_nop 1
	v_add_f32_dpp v84, v84, v84 row_bcast:31 row_mask:0xc bank_mask:0xf
	s_nop 1
	v_readlane_b32 s55, v84, 63
	s_nop 1
	v_mov_b32_e32 v85, s55
	v_mul_f32_e32 v85, 0x3a800000, v85
	v_sub_f32_e32 v52, v52, v85
	v_sub_f32_e32 v53, v53, v85
	v_sub_f32_e32 v54, v54, v85
	v_sub_f32_e32 v55, v55, v85
	v_sub_f32_e32 v56, v56, v85
	v_sub_f32_e32 v57, v57, v85
	v_sub_f32_e32 v58, v58, v85
	v_sub_f32_e32 v59, v59, v85
	v_sub_f32_e32 v60, v60, v85
	v_sub_f32_e32 v61, v61, v85
	v_sub_f32_e32 v62, v62, v85
	v_sub_f32_e32 v63, v63, v85
	v_sub_f32_e32 v64, v64, v85
	v_sub_f32_e32 v65, v65, v85
	v_sub_f32_e32 v66, v66, v85
	v_sub_f32_e32 v67, v67, v85
	v_mul_f32_e32 v88, v52, v52
	v_mul_f32_e32 v89, v53, v53
	v_mul_f32_e32 v90, v54, v54
	v_mul_f32_e32 v91, v55, v55
	v_fmac_f32_e32 v88, v56, v56
	v_fmac_f32_e32 v89, v57, v57
	v_fmac_f32_e32 v90, v58, v58
	v_fmac_f32_e32 v91, v59, v59
	v_fmac_f32_e32 v88, v60, v60
	v_fmac_f32_e32 v89, v61, v61
	v_fmac_f32_e32 v90, v62, v62
	v_fmac_f32_e32 v91, v63, v63
	v_fmac_f32_e32 v88, v64, v64
	v_fmac_f32_e32 v89, v65, v65
	v_fmac_f32_e32 v90, v66, v66
	v_fmac_f32_e32 v91, v67, v67
	v_add_f32_e32 v88, v88, v89
	v_add_f32_e32 v90, v90, v91
	v_add_f32_e32 v88, v88, v90
	s_nop 1
	v_add_f32_dpp v88, v88, v88 quad_perm:[1,0,3,2] row_mask:0xf bank_mask:0xf
	s_nop 1
	v_add_f32_dpp v88, v88, v88 quad_perm:[2,3,0,1] row_mask:0xf bank_mask:0xf
	s_nop 1
	v_add_f32_dpp v88, v88, v88 row_half_mirror row_mask:0xf bank_mask:0xf
	s_nop 1
	v_add_f32_dpp v88, v88, v88 row_mirror row_mask:0xf bank_mask:0xf
	s_nop 1
	v_add_f32_dpp v88, v88, v88 row_bcast:15 row_mask:0xa bank_mask:0xf
	s_nop 1
	v_add_f32_dpp v88, v88, v88 row_bcast:31 row_mask:0xc bank_mask:0xf
	s_nop 1
	v_readlane_b32 s55, v88, 63
	s_nop 1
	v_mov_b32_e32 v89, s55
	v_fmamk_f32 v89, v89, 0x3a800000, v214
	v_rsq_f32_e32 v90, v89
	s_nop 0
	v_mul_f32_e32 v91, v89, v90
	v_mul_f32_e32 v91, v91, v90
	v_mul_f32_e32 v91, -0.5, v91
	v_add_f32_e32 v91, 0x3fc00000, v91
	v_mul_f32_e32 v90, v90, v91
	v_pk_mul_f32 v[52:53], v[52:53], v[90:91] op_sel_hi:[1,0]
	v_pk_mul_f32 v[54:55], v[54:55], v[90:91] op_sel_hi:[1,0]
	v_pk_mul_f32 v[56:57], v[56:57], v[90:91] op_sel_hi:[1,0]
	v_pk_mul_f32 v[58:59], v[58:59], v[90:91] op_sel_hi:[1,0]
	v_pk_mul_f32 v[60:61], v[60:61], v[90:91] op_sel_hi:[1,0]
	v_pk_mul_f32 v[62:63], v[62:63], v[90:91] op_sel_hi:[1,0]
	v_pk_mul_f32 v[64:65], v[64:65], v[90:91] op_sel_hi:[1,0]
	v_pk_mul_f32 v[66:67], v[66:67], v[90:91] op_sel_hi:[1,0]
	v_pk_fma_f32 v[52:53], v[52:53], v[4:5], v[20:21]
	v_pk_fma_f32 v[54:55], v[54:55], v[6:7], v[22:23]
	v_pk_fma_f32 v[56:57], v[56:57], v[8:9], v[24:25]
	v_pk_fma_f32 v[58:59], v[58:59], v[10:11], v[26:27]
	v_pk_fma_f32 v[60:61], v[60:61], v[12:13], v[28:29]
	v_pk_fma_f32 v[62:63], v[62:63], v[14:15], v[30:31]
	v_pk_fma_f32 v[64:65], v[64:65], v[16:17], v[32:33]
	v_pk_fma_f32 v[66:67], v[66:67], v[18:19], v[34:35]
	v_cvt_pk_bf16_f32 v100, v52, v53
	v_cvt_pk_bf16_f32 v101, v54, v55
	v_cvt_pk_bf16_f32 v102, v56, v57
	v_cvt_pk_bf16_f32 v103, v58, v59
	v_cvt_pk_bf16_f32 v104, v60, v61
	v_cvt_pk_bf16_f32 v105, v62, v63
	v_cvt_pk_bf16_f32 v106, v64, v65
	v_cvt_pk_bf16_f32 v107, v66, v67
	global_store_dwordx4 v2, v[52:55], s[8:9] nt
	global_store_dwordx4 v2, v[56:59], s[8:9] offset:1024 nt
	global_store_dwordx4 v2, v[60:63], s[8:9] offset:2048 nt
	global_store_dwordx4 v2, v[64:67], s[8:9] offset:3072 nt
	global_store_dwordx2 v3, v[100:101], s[10:11] nt
	global_store_dwordx2 v3, v[102:103], s[10:11] offset:512 nt
	global_store_dwordx2 v3, v[104:105], s[10:11] offset:1024 nt
	global_store_dwordx2 v3, v[106:107], s[10:11] offset:1536 nt
	s_add_u32 s8, s8, s34
	s_addc_u32 s9, s9, 0
	s_add_u32 s10, s10, s35
	s_addc_u32 s11, s11, 0
	s_add_i32 s4, s4, s5
	s_cmp_ge_i32 s4, 0x8000
	s_cbranch_scc1 .Lmy_lnp1_done

; DI unsigned cvtpk(float lo, float hi) { f32x2_t v = {lo, hi}; bf16x2_t b = __builtin_convertvector(v, bf16x2_t); return __builtin_bit_cast(unsigned, b); }
; DI void ln_row(float* yrow, bf16_t* xb, const float* g, const float* b, int lane, float* yout = nullptr) {
;     f32x4* xr = (f32x4*)yrow + lane; f32x4* xo = yout ? (f32x4*)yout + lane : xr;
;     f32x4 v[4]; float s = 0.f;
; #pragma unroll
;     for (int j = 0; j < 4; ++j) { v[j] = xr[64 * j]; s += (v[j].x + v[j].y) + (v[j].z + v[j].w); }
;     const float mean = wave_sum(s) * (1.f / DM); float s2 = 0.f;
; #pragma unroll
;     for (int j = 0; j < 4; ++j) { v[j] = v[j] - mean; s2 += (v[j].x * v[j].x + v[j].y * v[j].y) + (v[j].z * v[j].z + v[j].w * v[j].w); }
;     const float rstd = 1.f / sqrtf(wave_sum(s2) * (1.f / DM) + EPS);
;     u32x2* o8 = (u32x2*)xb + lane;
; #pragma unroll
;     for (int j = 0; j < 4; ++j) {
;         const f32x4 gg = ((const f32x4*)g)[lane + 64 * j], bb = ((const f32x4*)b)[lane + 64 * j];
;         const f32x4 o = v[j] * rstd * gg + bb;
;         xo[64 * j] = o;
;         u32x2 w; w.x = cvtpk(o.x, o.y); w.y = cvtpk(o.z, o.w); o8[64 * j] = w;
;     }
; }
; DI void ln_phase(unsigned char* lds, int l, int which) {
;     ...
;         int m = gw;
;         for (; m + NGW < MP; m += 2 * NGW) ln_row2(Y + (size_t)m * DM, Y + (size_t)(m + NGW) * DM, XB + (size_t)m * DM, XB + (size_t)(m + NGW) * DM, g, b, lane);
;         if (m < MP) ln_row(Y + (size_t)m * DM, XB + (size_t)m * DM, g, b, lane);
.Lmy_lnp1_n2:
	s_add_i32 s100, s56, 0
	s_min_u32 s100, s100, 15
	s_lshl_b32 s100, s100, 7
	s_add_u32 s100, s48, s100
	s_addc_u32 s101, s49, 0
	global_load_dwordx4 v[110:113], v108, s[100:101]
	s_add_i32 s100, s56, 4
	s_min_u32 s100, s100, 15
	s_lshl_b32 s100, s100, 7
	s_add_u32 s100, s48, s100
	s_addc_u32 s101, s49, 0
	global_load_dwordx4 v[110:113], v108, s[100:101]
	s_add_i32 s56, s56, 4
	s_waitcnt vmcnt(20)
	v_add_f32_e32 v84, v68, v69
	v_add_f32_e32 v85, v70, v71
	v_add_f32_e32 v86, v72, v73
	v_add_f32_e32 v87, v74, v75
	v_add_f32_e32 v88, v76, v77
	v_add_f32_e32 v89, v78, v79
	v_add_f32_e32 v90, v80, v81
	v_add_f32_e32 v91, v82, v83
	v_add_f32_e32 v84, v84, v85
	v_add_f32_e32 v86, v86, v87
	v_add_f32_e32 v88, v88, v89
	v_add_f32_e32 v90, v90, v91
	v_add_f32_e32 v84, v84, v86
	v_add_f32_e32 v88, v88, v90
	v_add_f32_e32 v84, v84, v88
	s_nop 1
	v_add_f32_dpp v84, v84, v84 quad_perm:[1,0,3,2] row_mask:0xf bank_mask:0xf
	s_nop 1
	v_add_f32_dpp v84, v84, v84 quad_perm:[2,3,0,1] row_mask:0xf bank_mask:0xf
	s_nop 1
	v_add_f32_dpp v84, v84, v84 row_half_mirror row_mask:0xf bank_mask:0xf
	s_nop 1
	v_add_f32_dpp v84, v84, v84 row_mirror row_mask:0xf bank_mask:0xf
	s_nop 1
	v_add_f32_dpp v84, v84, v84 row_bcast:15 row_mask:0xa bank_mask:0xf
	s_nop 1
	v_add_f32_dpp v84, v84, v84 row_bcast:31 row_mask:0xc bank_mask:0xf
	s_nop 1
	v_readlane_b32 s55, v84, 63
	s_nop 1
	v_mov_b32_e32 v85, s55
	v_mul_f32_e32 v85, 0x3a800000, v85
	v_sub_f32_e32 v68, v68, v85
	v_sub_f32_e32 v69, v69, v85
	v_sub_f32_e32 v70, v70, v85
	v_sub_f32_e32 v71, v71, v85
	v_sub_f32_e32 v72, v72, v85
	v_sub_f32_e32 v73, v73, v85
	v_sub_f32_e32 v74, v74, v85
	v_sub_f32_e32 v75, v75, v85
	v_sub_f32_e32 v76, v76, v85
	v_sub_f32_e32 v77, v77, v85
	v_sub_f32_e32 v78, v78, v85
	v_sub_f32_e32 v79, v79, v85
	v_sub_f32_e32 v80, v80, v85
	v_sub_f32_e32 v81, v81, v85
	v_sub_f32_e32 v82, v82, v85
	v_sub_f32_e32 v83, v83, v85
	v_mul_f32_e32 v88, v68, v68
	v_mul_f32_e32 v89, v69, v69
	v_mul_f32_e32 v90, v70, v70
	v_mul_f32_e32 v91, v71, v71
	v_fmac_f32_e32 v88, v72, v72
	v_fmac_f32_e32 v89, v73, v73
	v_fmac_f32_e32 v90, v74, v74
	v_fmac_f32_e32 v91, v75, v75
	v_fmac_f32_e32 v88, v76, v76
	v_fmac_f32_e32 v89, v77, v77
	v_fmac_f32_e32 v90, v78, v78
	v_fmac_f32_e32 v91, v79, v79
	v_fmac_f32_e32 v88, v80, v80
	v_fmac_f32_e32 v89, v81, v81
	v_fmac_f32_e32 v90, v82, v82
	v_fmac_f32_e32 v91, v83, v83
	v_add_f32_e32 v88, v88, v89
	v_add_f32_e32 v90, v90, v91
	v_add_f32_e32 v88, v88, v90
	s_nop 1
	v_add_f32_dpp v88, v88, v88 quad_perm:[1,0,3,2] row_mask:0xf bank_mask:0xf
	s_nop 1
	v_add_f32_dpp v88, v88, v88 quad_perm:[2,3,0,1] row_mask:0xf bank_mask:0xf
	s_nop 1
	v_add_f32_dpp v88, v88, v88 row_half_mirror row_mask:0xf bank_mask:0xf
	s_nop 1
	v_add_f32_dpp v88, v88, v88 row_mirror row_mask:0xf bank_mask:0xf
	s_nop 1
	v_add_f32_dpp v88, v88, v88 row_bcast:15 row_mask:0xa bank_mask:0xf
	s_nop 1
	v_add_f32_dpp v88, v88, v88 row_bcast:31 row_mask:0xc bank_mask:0xf
	s_nop 1
	v_readlane_b32 s55, v88, 63
	s_nop 1
	v_mov_b32_e32 v89, s55
	v_fmamk_f32 v89, v89, 0x3a800000, v214
	v_rsq_f32_e32 v90, v89
	s_nop 0
	v_mul_f32_e32 v91, v89, v90
	v_mul_f32_e32 v91, v91, v90
	v_mul_f32_e32 v91, -0.5, v91
	v_add_f32_e32 v91, 0x3fc00000, v91
	v_mul_f32_e32 v90, v90, v91
	v_pk_mul_f32 v[68:69], v[68:69], v[90:91] op_sel_hi:[1,0]
	v_pk_mul_f32 v[70:71], v[70:71], v[90:91] op_sel_hi:[1,0]
	v_pk_mul_f32 v[72:73], v[72:73], v[90:91] op_sel_hi:[1,0]
	v_pk_mul_f32 v[74:75], v[74:75], v[90:91] op_sel_hi:[1,0]
	v_pk_mul_f32 v[76:77], v[76:77], v[90:91] op_sel_hi:[1,0]
	v_pk_mul_f32 v[78:79], v[78:79], v[90:91] op_sel_hi:[1,0]
	v_pk_mul_f32 v[80:81], v[80:81], v[90:91] op_sel_hi:[1,0]
	v_pk_mul_f32 v[82:83], v[82:83], v[90:91] op_sel_hi:[1,0]
	v_pk_fma_f32 v[68:69], v[68:69], v[4:5], v[20:21]
	v_pk_fma_f32 v[70:71], v[70:71], v[6:7], v[22:23]
	v_pk_fma_f32 v[72:73], v[72:73], v[8:9], v[24:25]
	v_pk_fma_f32 v[74:75], v[74:75], v[10:11], v[26:27]
	v_pk_fma_f32 v[76:77], v[76:77], v[12:13], v[28:29]
	v_pk_fma_f32 v[78:79], v[78:79], v[14:15], v[30:31]
	v_pk_fma_f32 v[80:81], v[80:81], v[16:17], v[32:33]
	v_pk_fma_f32 v[82:83], v[82:83], v[18:19], v[34:35]
	v_cvt_pk_bf16_f32 v100, v68, v69
	v_cvt_pk_bf16_f32 v101, v70, v71
	v_cvt_pk_bf16_f32 v102, v72, v73
	v_cvt_pk_bf16_f32 v103, v74, v75
	v_cvt_pk_bf16_f32 v104, v76, v77
	v_cvt_pk_bf16_f32 v105, v78, v79
	v_cvt_pk_bf16_f32 v106, v80, v81
	v_cvt_pk_bf16_f32 v107, v82, v83
	global_store_dwordx4 v2, v[68:71], s[8:9] nt
	global_store_dwordx4 v2, v[72:75], s[8:9] offset:1024 nt
	global_store_dwordx4 v2, v[76:79], s[8:9] offset:2048 nt
	global_store_dwordx4 v2, v[80:83], s[8:9] offset:3072 nt
	global_store_dwordx2 v3, v[100:101], s[10:11] nt
	global_store_dwordx2 v3, v[102:103], s[10:11] offset:512 nt
	global_store_dwordx2 v3, v[104:105], s[10:11] offset:1024 nt
	global_store_dwordx2 v3, v[106:107], s[10:11] offset:1536 nt
	s_add_u32 s8, s8, s34
	s_addc_u32 s9, s9, 0
	s_add_u32 s10, s10, s35
	s_addc_u32 s11, s11, 0
	s_add_i32 s4, s4, s5
	s_cmp_ge_i32 s4, 0x8000
	s_cbranch_scc1 .Lmy_lnp1_done
	s_branch .Lmy_lnp1_b0
